# D attention unit epilogue: sub-layer-norm gain loads batched; the 16 row-per-lane 8-byte stores paired into 8 16-byte stores with v_permlane32_swap (same bytes, same addresses)
# baseline (speedup 1.0000x reference)
; #define LAS __attribute__((address_space(3)))
; DI float shx(float v, int m, int lane) { return __builtin_bit_cast(float, __builtin_amdgcn_ds_bpermute((lane ^ m) << 2, __builtin_bit_cast(int, v))); }
; DI void attn_unit_d32(const Ctx& C, const bf16_t* __restrict__ Z, bf16_t* __restrict__ Y, int b, int qsel, int hsel, bool ctxq, float lam, float post_scale, const float* subln, const float mref) {
;     ...
;     float l = lsum; l += shx(l, 32, lane); const float linv = 1.f / l;
;     LAS float* X = (LAS float*)C.lds + (32 * qg + l31) * 132;
;     if (sm == 1) {
; #pragma unroll
;         for (int d = 0; d < 4; ++d)
; #pragma unroll
;             for (int g = 0; g < 4; ++g) { const f32x4 v = {o[d][4 * g] * linv, o[d][4 * g + 1] * linv, o[d][4 * g + 2] * linv, o[d][4 * g + 3] * linv};
;                 *(LAS f32x4*)(X + 32 * d + 8 * g + 4 * hh) = v; }
;     }
;     __syncthreads();
;     if (sm == 0) {
;         f32x4 r[4][4]; float ss = 0.f;
; #pragma unroll
;         for (int d = 0; d < 4; ++d)
; #pragma unroll
;             for (int g = 0; g < 4; ++g) { const f32x4 x2 = *(const LAS f32x4*)(X + 32 * d + 8 * g + 4 * hh);
;                 const f32x4 x1 = {o[d][4 * g] * linv, o[d][4 * g + 1] * linv, o[d][4 * g + 2] * linv, o[d][4 * g + 3] * linv};
;                 r[d][g] = x1 - x2 * lam; ss += (r[d][g][0] * r[d][g][0] + r[d][g][1] * r[d][g][1]) + (r[d][g][2] * r[d][g][2] + r[d][g][3] * r[d][g][3]); }
;         ss += shx(ss, 32, lane);
.LBB0_410:
	s_andn2_b64 vcc, exec, s[14:15]
	s_waitcnt lgkmcnt(0)
	s_barrier
	s_cbranch_vccnz .LBB0_396
	ds_read_b128 v[84:87], v190
	ds_read_b128 v[98:101], v190 offset:32
	v_xor_b32_e32 v96, 0x80000000, v168
	v_pk_mul_f32 v[68:69], v[68:69], v[0:1] op_sel_hi:[1,0]
	v_pk_mul_f32 v[70:71], v[70:71], v[0:1] op_sel_hi:[1,0]
	v_mov_b32_e32 v97, v96
	s_waitcnt lgkmcnt(1)
	v_pk_fma_f32 v[92:93], v[96:97], v[86:87], v[70:71]
	v_pk_fma_f32 v[94:95], v[168:169], v[84:85], v[68:69] neg_lo:[1,0,0] neg_hi:[1,0,0]
	v_pk_mul_f32 v[68:69], v[92:93], v[92:93]
	v_pk_mul_f32 v[70:71], v[94:95], v[94:95]
	v_pk_mul_f32 v[52:53], v[52:53], v[0:1] op_sel_hi:[1,0]
	v_pk_mov_b32 v[84:85], v[70:71], v[68:69] op_sel:[1,0]
	v_mov_b32_e32 v71, v69
	v_pk_add_f32 v[102:103], v[84:85], v[70:71]
	v_pk_mul_f32 v[68:69], v[72:73], v[0:1] op_sel_hi:[1,0]
	v_pk_mul_f32 v[70:71], v[74:75], v[0:1] op_sel_hi:[1,0]
	s_waitcnt lgkmcnt(0)
	v_pk_fma_f32 v[90:91], v[168:169], v[98:99], v[68:69] neg_lo:[1,0,0] neg_hi:[1,0,0]
	v_pk_fma_f32 v[88:89], v[96:97], v[100:101], v[70:71]
	v_pk_mul_f32 v[70:71], v[90:91], v[90:91]
	v_pk_mul_f32 v[68:69], v[88:89], v[88:89]
	v_pk_mul_f32 v[74:75], v[76:77], v[0:1] op_sel_hi:[1,0]
	v_pk_mov_b32 v[72:73], v[70:71], v[68:69] op_sel:[1,0]
	v_mov_b32_e32 v71, v69
	v_pk_add_f32 v[72:73], v[72:73], v[70:71]
	ds_read_b128 v[68:71], v190 offset:64
	v_pk_mul_f32 v[76:77], v[78:79], v[0:1] op_sel_hi:[1,0]
	v_pk_mul_f32 v[54:55], v[54:55], v[0:1] op_sel_hi:[1,0]
	v_pk_mul_f32 v[56:57], v[56:57], v[0:1] op_sel_hi:[1,0]
	v_pk_mul_f32 v[58:59], v[58:59], v[0:1] op_sel_hi:[1,0]
	s_waitcnt lgkmcnt(0)
	v_pk_fma_f32 v[84:85], v[96:97], v[70:71], v[76:77]
	v_pk_fma_f32 v[86:87], v[168:169], v[68:69], v[74:75] neg_lo:[1,0,0] neg_hi:[1,0,0]
	ds_read_b128 v[68:71], v190 offset:96
	v_pk_mul_f32 v[74:75], v[80:81], v[0:1] op_sel_hi:[1,0]
	v_pk_mul_f32 v[76:77], v[82:83], v[0:1] op_sel_hi:[1,0]
	v_pk_mul_f32 v[36:37], v[36:37], v[0:1] op_sel_hi:[1,0]
	v_pk_mul_f32 v[38:39], v[38:39], v[0:1] op_sel_hi:[1,0]
	s_waitcnt lgkmcnt(0)
	v_pk_fma_f32 v[78:79], v[168:169], v[68:69], v[74:75] neg_lo:[1,0,0] neg_hi:[1,0,0]
	v_pk_fma_f32 v[76:77], v[96:97], v[70:71], v[76:77]
	v_mul_f32_e32 v70, v78, v78
	v_pk_add_f32 v[68:69], v[102:103], v[102:103] op_sel:[0,1] op_sel_hi:[1,0]
	v_mul_f32_e32 v74, v79, v79
	v_mov_b32_e32 v69, v70
	v_pk_add_f32 v[70:71], v[72:73], v[72:73] op_sel:[0,1] op_sel_hi:[1,0]
	v_mul_f32_e32 v72, v85, v85
	v_mov_b32_e32 v71, v74
	v_pk_add_f32 v[68:69], v[68:69], v[70:71]
	v_mul_f32_e32 v70, v87, v87
	v_mul_f32_e32 v75, v76, v76
	v_mul_f32_e32 v80, v77, v77
	v_pk_fma_f32 v[70:71], v[86:87], v[86:87], v[70:71] op_sel_hi:[1,1,0]
	v_pk_fma_f32 v[72:73], v[84:85], v[84:85], v[72:73] op_sel_hi:[1,1,0]
	v_mov_b32_e32 v71, v75
	v_mov_b32_e32 v73, v80
	v_pk_add_f32 v[70:71], v[70:71], v[72:73]
	v_pk_mul_f32 v[40:41], v[40:41], v[0:1] op_sel_hi:[1,0]
	v_pk_add_f32 v[80:81], v[68:69], v[70:71]
	ds_read_b128 v[70:73], v190 offset:128
	v_pk_mul_f32 v[42:43], v[42:43], v[0:1] op_sel_hi:[1,0]
	v_pk_mul_f32 v[24:25], v[24:25], v[0:1] op_sel_hi:[1,0]
	v_pk_mul_f32 v[26:27], v[26:27], v[0:1] op_sel_hi:[1,0]
	v_pk_mul_f32 v[28:29], v[28:29], v[0:1] op_sel_hi:[1,0]
	s_waitcnt lgkmcnt(0)
	v_pk_fma_f32 v[68:69], v[96:97], v[72:73], v[54:55]
	v_pk_fma_f32 v[70:71], v[168:169], v[70:71], v[52:53] neg_lo:[1,0,0] neg_hi:[1,0,0]
	v_pk_mul_f32 v[52:53], v[68:69], v[68:69]
	v_pk_mul_f32 v[54:55], v[70:71], v[70:71]
	v_pk_mul_f32 v[30:31], v[30:31], v[0:1] op_sel_hi:[1,0]
	v_pk_mov_b32 v[72:73], v[54:55], v[52:53] op_sel:[1,0]
	v_mov_b32_e32 v55, v53
	v_pk_add_f32 v[82:83], v[72:73], v[54:55]
	ds_read_b128 v[52:55], v190 offset:160
	v_pk_mul_f32 v[32:33], v[32:33], v[0:1] op_sel_hi:[1,0]
	s_lshl_b32 s36, s21, 1
	s_waitcnt lgkmcnt(0)
	v_pk_fma_f32 v[72:73], v[96:97], v[54:55], v[58:59]
	v_pk_fma_f32 v[74:75], v[168:169], v[52:53], v[56:57] neg_lo:[1,0,0] neg_hi:[1,0,0]
	ds_read_b128 v[54:57], v190 offset:192
	v_pk_mul_f32 v[58:59], v[60:61], v[0:1] op_sel_hi:[1,0]
	v_pk_mul_f32 v[52:53], v[62:63], v[0:1] op_sel_hi:[1,0]
	s_waitcnt lgkmcnt(0)
	v_pk_fma_f32 v[54:55], v[168:169], v[54:55], v[58:59] neg_lo:[1,0,0] neg_hi:[1,0,0]
	v_pk_fma_f32 v[52:53], v[96:97], v[56:57], v[52:53]
	v_mul_f32_e32 v58, v54, v54
	v_pk_add_f32 v[56:57], v[80:81], v[80:81] op_sel:[0,1] op_sel_hi:[1,0]
	v_mul_f32_e32 v60, v55, v55
	v_mov_b32_e32 v57, v58
	v_pk_add_f32 v[58:59], v[82:83], v[82:83] op_sel:[0,1] op_sel_hi:[1,0]
	v_mul_f32_e32 v61, v52, v52
	v_mov_b32_e32 v59, v60
	v_pk_add_f32 v[56:57], v[56:57], v[58:59]
	v_mul_f32_e32 v58, v75, v75
	v_pk_fma_f32 v[58:59], v[74:75], v[74:75], v[58:59] op_sel_hi:[1,1,0]
	v_mul_f32_e32 v60, v73, v73
	v_mul_f32_e32 v62, v53, v53
	v_mov_b32_e32 v59, v61
	v_pk_fma_f32 v[60:61], v[72:73], v[72:73], v[60:61] op_sel_hi:[1,1,0]
	s_nop 0
	v_mov_b32_e32 v61, v62
	v_pk_add_f32 v[58:59], v[58:59], v[60:61]
	v_pk_mul_f32 v[60:61], v[64:65], v[0:1] op_sel_hi:[1,0]
	v_pk_add_f32 v[80:81], v[56:57], v[58:59]
	ds_read_b128 v[56:59], v190 offset:224
	v_pk_mul_f32 v[62:63], v[66:67], v[0:1] op_sel_hi:[1,0]
	s_waitcnt lgkmcnt(0)
	v_pk_fma_f32 v[66:67], v[168:169], v[56:57], v[60:61] neg_lo:[1,0,0] neg_hi:[1,0,0]
	v_pk_fma_f32 v[64:65], v[96:97], v[58:59], v[62:63]
	v_pk_mul_f32 v[58:59], v[66:67], v[66:67]
	v_pk_mul_f32 v[56:57], v[64:65], v[64:65]
	s_nop 0
	v_pk_mov_b32 v[60:61], v[58:59], v[56:57] op_sel:[1,0]
	v_mov_b32_e32 v59, v57
	v_pk_add_f32 v[82:83], v[60:61], v[58:59]
	ds_read_b128 v[56:59], v190 offset:256
	s_waitcnt lgkmcnt(0)
	v_pk_fma_f32 v[60:61], v[96:97], v[58:59], v[38:39]
	v_pk_fma_f32 v[62:63], v[168:169], v[56:57], v[36:37] neg_lo:[1,0,0] neg_hi:[1,0,0]
	ds_read_b128 v[36:39], v190 offset:288
	s_waitcnt lgkmcnt(0)
; #define LAS __attribute__((address_space(3)))
; DI float shx(float v, int m, int lane) { return __builtin_bit_cast(float, __builtin_amdgcn_ds_bpermute((lane ^ m) << 2, __builtin_bit_cast(int, v))); }
; DI void attn_unit_d32(const Ctx& C, const bf16_t* __restrict__ Z, bf16_t* __restrict__ Y, int b, int qsel, int hsel, bool ctxq, float lam, float post_scale, const float* subln, const float mref) {
;     ...
;         f32x4 r[4][4]; float ss = 0.f;
; #pragma unroll
;         for (int d = 0; d < 4; ++d)
; #pragma unroll
;             for (int g = 0; g < 4; ++g) { const f32x4 x2 = *(const LAS f32x4*)(X + 32 * d + 8 * g + 4 * hh);
;                 const f32x4 x1 = {o[d][4 * g] * linv, o[d][4 * g + 1] * linv, o[d][4 * g + 2] * linv, o[d][4 * g + 3] * linv};
;                 r[d][g] = x1 - x2 * lam; ss += (r[d][g][0] * r[d][g][0] + r[d][g][1] * r[d][g][1]) + (r[d][g][2] * r[d][g][2] + r[d][g][3] * r[d][g][3]); }
;         ss += shx(ss, 32, lane);
	v_pk_fma_f32 v[58:59], v[168:169], v[36:37], v[40:41] neg_lo:[1,0,0] neg_hi:[1,0,0]
	v_pk_fma_f32 v[56:57], v[96:97], v[38:39], v[42:43]
	v_mul_f32_e32 v38, v58, v58
	v_pk_add_f32 v[36:37], v[80:81], v[80:81] op_sel:[0,1] op_sel_hi:[1,0]
	v_mul_f32_e32 v40, v59, v59
	v_mov_b32_e32 v37, v38
	v_pk_add_f32 v[38:39], v[82:83], v[82:83] op_sel:[0,1] op_sel_hi:[1,0]
	v_mul_f32_e32 v41, v56, v56
	v_mov_b32_e32 v39, v40
	v_pk_add_f32 v[36:37], v[36:37], v[38:39]
	v_mul_f32_e32 v38, v63, v63
	v_pk_fma_f32 v[38:39], v[62:63], v[62:63], v[38:39] op_sel_hi:[1,1,0]
	v_mul_f32_e32 v40, v61, v61
	v_mul_f32_e32 v42, v57, v57
	v_mov_b32_e32 v39, v41
	v_pk_fma_f32 v[40:41], v[60:61], v[60:61], v[40:41] op_sel_hi:[1,1,0]
	s_nop 0
	v_mov_b32_e32 v41, v42
	v_pk_add_f32 v[38:39], v[38:39], v[40:41]
	v_pk_mul_f32 v[42:43], v[44:45], v[0:1] op_sel_hi:[1,0]
	v_pk_add_f32 v[80:81], v[36:37], v[38:39]
	ds_read_b128 v[36:39], v190 offset:320
	v_pk_mul_f32 v[40:41], v[46:47], v[0:1] op_sel_hi:[1,0]
	s_waitcnt lgkmcnt(0)
	v_pk_fma_f32 v[42:43], v[168:169], v[36:37], v[42:43] neg_lo:[1,0,0] neg_hi:[1,0,0]
	v_pk_fma_f32 v[40:41], v[96:97], v[38:39], v[40:41]
	v_pk_mul_f32 v[38:39], v[42:43], v[42:43]
	v_pk_mul_f32 v[36:37], v[40:41], v[40:41]
	s_nop 0
	v_pk_mov_b32 v[44:45], v[38:39], v[36:37] op_sel:[1,0]
	v_mov_b32_e32 v39, v37
	v_pk_add_f32 v[82:83], v[44:45], v[38:39]
	ds_read_b128 v[44:47], v190 offset:352
	v_pk_mul_f32 v[38:39], v[48:49], v[0:1] op_sel_hi:[1,0]
	v_pk_mul_f32 v[36:37], v[50:51], v[0:1] op_sel_hi:[1,0]
	v_pk_mul_f32 v[48:49], v[20:21], v[0:1] op_sel_hi:[1,0]
	v_pk_mul_f32 v[20:21], v[22:23], v[0:1] op_sel_hi:[1,0]
	s_waitcnt lgkmcnt(0)
	v_pk_fma_f32 v[36:37], v[96:97], v[46:47], v[36:37]
	v_pk_fma_f32 v[38:39], v[168:169], v[44:45], v[38:39] neg_lo:[1,0,0] neg_hi:[1,0,0]
	ds_read_b128 v[44:47], v190 offset:384
	s_waitcnt lgkmcnt(0)
	v_pk_fma_f32 v[22:23], v[168:169], v[44:45], v[48:49] neg_lo:[1,0,0] neg_hi:[1,0,0]
	v_pk_fma_f32 v[20:21], v[96:97], v[46:47], v[20:21]
	v_mul_f32_e32 v46, v22, v22
	v_pk_add_f32 v[44:45], v[80:81], v[80:81] op_sel:[0,1] op_sel_hi:[1,0]
	v_mul_f32_e32 v48, v23, v23
	v_mov_b32_e32 v45, v46
	v_pk_add_f32 v[46:47], v[82:83], v[82:83] op_sel:[0,1] op_sel_hi:[1,0]
	v_mul_f32_e32 v49, v20, v20
	v_mov_b32_e32 v47, v48
	v_pk_add_f32 v[44:45], v[44:45], v[46:47]
	v_mul_f32_e32 v46, v39, v39
	v_pk_fma_f32 v[46:47], v[38:39], v[38:39], v[46:47] op_sel_hi:[1,1,0]
	v_mul_f32_e32 v48, v37, v37
	v_mul_f32_e32 v50, v21, v21
	v_mov_b32_e32 v47, v49
	v_pk_fma_f32 v[48:49], v[36:37], v[36:37], v[48:49] op_sel_hi:[1,1,0]
	s_nop 0
	v_mov_b32_e32 v49, v50
	v_pk_add_f32 v[46:47], v[46:47], v[48:49]
	s_nop 0
	v_pk_add_f32 v[50:51], v[44:45], v[46:47]
	ds_read_b128 v[44:47], v190 offset:416
	s_waitcnt lgkmcnt(0)
	v_pk_fma_f32 v[46:47], v[96:97], v[46:47], v[26:27]
	v_pk_fma_f32 v[48:49], v[168:169], v[44:45], v[24:25] neg_lo:[1,0,0] neg_hi:[1,0,0]
	v_pk_mul_f32 v[24:25], v[46:47], v[46:47]
	v_pk_mul_f32 v[26:27], v[48:49], v[48:49]
	s_nop 0
	v_pk_mov_b32 v[44:45], v[26:27], v[24:25] op_sel:[1,0]
	v_mov_b32_e32 v27, v25
	v_pk_add_f32 v[80:81], v[44:45], v[26:27]
	ds_read_b128 v[24:27], v190 offset:448
	s_waitcnt lgkmcnt(0)
	v_pk_fma_f32 v[30:31], v[96:97], v[26:27], v[30:31]
	v_pk_fma_f32 v[44:45], v[168:169], v[24:25], v[28:29] neg_lo:[1,0,0] neg_hi:[1,0,0]
	ds_read_b128 v[26:29], v190 offset:480
	v_pk_mul_f32 v[24:25], v[34:35], v[0:1] op_sel_hi:[1,0]
	s_waitcnt lgkmcnt(0)
	v_pk_fma_f32 v[26:27], v[168:169], v[26:27], v[32:33] neg_lo:[1,0,0] neg_hi:[1,0,0]
	v_pk_fma_f32 v[24:25], v[96:97], v[28:29], v[24:25]
	v_mul_f32_e32 v0, v26, v26
	v_mul_f32_e32 v34, v27, v27
	v_pk_add_f32 v[28:29], v[50:51], v[50:51] op_sel:[0,1] op_sel_hi:[1,0]
	v_pk_add_f32 v[32:33], v[80:81], v[80:81] op_sel:[0,1] op_sel_hi:[1,0]
	v_mov_b32_e32 v29, v0
	v_mov_b32_e32 v33, v34
	v_mul_f32_e32 v0, v45, v45
	v_mul_f32_e32 v35, v24, v24
	v_pk_add_f32 v[28:29], v[28:29], v[32:33]
	v_pk_fma_f32 v[32:33], v[44:45], v[44:45], v[0:1] op_sel_hi:[1,1,0]
	v_mul_f32_e32 v0, v31, v31
	v_mul_f32_e32 v82, v25, v25
	v_mov_b32_e32 v33, v35
	v_pk_fma_f32 v[34:35], v[30:31], v[30:31], v[0:1] op_sel_hi:[1,1,0]
	s_nop 0
	v_mov_b32_e32 v35, v82
	v_pk_add_f32 v[32:33], v[32:33], v[34:35]
	s_nop 0
	v_pk_add_f32 v[28:29], v[28:29], v[32:33]
	s_nop 0
	v_add_f32_e32 v0, v28, v29
	ds_bpermute_b32 v28, v186, v0
	s_waitcnt lgkmcnt(0)
; #define GAS __attribute__((address_space(1)))
; DI unsigned pk2(float lo, float hi) { f32x2 v = {lo, hi}; bf16x2_t b = __builtin_convertvector(v, bf16x2_t); return __builtin_bit_cast(unsigned, b); }
; DI float shx(float v, int m, int lane) { return __builtin_bit_cast(float, __builtin_amdgcn_ds_bpermute((lane ^ m) << 2, __builtin_bit_cast(int, v))); }
; DI void attn_unit_d32(const Ctx& C, const bf16_t* __restrict__ Z, bf16_t* __restrict__ Y, int b, int qsel, int hsel, bool ctxq, float lam, float post_scale, const float* subln, const float mref) {
;     ...
;         ss += shx(ss, 32, lane);
;         const float rs = post_scale / sqrtf(ss * (1.f / 128.f) + EPS);
;         bf16_t* yp = Y + (size_t)qrow * DM + ycol;
; #pragma unroll
;         for (int d = 0; d < 4; ++d)
; #pragma unroll
;             for (int g = 0; g < 4; ++g) { const int dv = 32 * d + 8 * g + 4 * hh; const f32x4 gn = *(const GAS f32x4*)(subln + dv); const f32x4 v = r[d][g] * rs * gn;
;                 u32x2 wv; wv.x = pk2(v[0], v[1]); wv.y = pk2(v[2], v[3]); *(GAS u32x2*)(yp + dv) = wv; }
	v_add_f32_e32 v0, v0, v28
	v_fmamk_f32 v0, v0, 0x3c000000, v227
	v_cmp_gt_f32_e32 vcc, s67, v0
	v_mul_f32_e32 v28, 0x4f800000, v0
	s_nop 0
	v_cndmask_b32_e32 v0, v0, v28, vcc
	v_sqrt_f32_e32 v28, v0
	s_nop 0
	v_add_u32_e32 v29, -1, v28
	v_fma_f32 v32, -v29, v28, v0
	v_cmp_ge_f32_e64 s[0:1], 0, v32
	v_add_u32_e32 v32, 1, v28
	s_nop 0
	v_cndmask_b32_e64 v29, v28, v29, s[0:1]
	v_fma_f32 v28, -v32, v28, v0
	v_cmp_lt_f32_e64 s[0:1], 0, v28
	s_nop 1
	v_cndmask_b32_e64 v28, v29, v32, s[0:1]
	v_mul_f32_e32 v29, 0x37800000, v28
	v_cndmask_b32_e32 v28, v28, v29, vcc
	v_cmp_class_f32_e32 vcc, v0, v228
	s_nop 1
	v_cndmask_b32_e32 v0, v28, v0, vcc
	v_div_scale_f32 v28, s[0:1], v0, v0, v176
	v_rcp_f32_e32 v29, v28
	s_nop 0
	v_fma_f32 v32, -v28, v29, 1.0
	v_fmac_f32_e32 v29, v32, v29
	v_div_scale_f32 v32, vcc, v176, v0, v176
	v_mul_f32_e32 v33, v32, v29
	v_fma_f32 v34, -v28, v33, v32
	v_fmac_f32_e32 v33, v34, v29
	v_fma_f32 v28, -v28, v33, v32
	v_div_fmas_f32 v28, v28, v29, v33
	global_load_dwordx4 v[140:143], v[170:171], off
	global_load_dwordx4 v[144:147], v[170:171], off offset:32
	global_load_dwordx4 v[148:151], v[170:171], off offset:64
	global_load_dwordx4 v[152:155], v[170:171], off offset:96
	global_load_dwordx4 v[158:161], v[170:171], off offset:128
	global_load_dwordx4 v[192:195], v[170:171], off offset:160
	global_load_dwordx4 v[202:205], v[170:171], off offset:192
	global_load_dwordx4 v[210:213], v[170:171], off offset:224
	global_load_dwordx4 v[214:217], v[170:171], off offset:256
	global_load_dwordx4 v[218:221], v[170:171], off offset:288
	global_load_dwordx4 v[222:225], v[170:171], off offset:320
	global_load_dwordx4 v[240:243], v[170:171], off offset:352
	global_load_dwordx4 v[244:247], v[170:171], off offset:384
	v_div_fixup_f32 v0, v28, v0, v176
	v_lshlrev_b64 v[28:29], 12, v[172:173]
	v_lshl_add_u64 v[28:29], s[10:11], 0, v[28:29]
	v_pk_mul_f32 v[50:51], v[94:95], v[0:1] op_sel_hi:[1,0]
	v_pk_mul_f32 v[80:81], v[92:93], v[0:1] op_sel_hi:[1,0]
	v_lshl_add_u64 v[28:29], v[28:29], 0, s[36:37]
	v_lshl_add_u64 v[28:29], v[166:167], 1, v[28:29]
	v_mbcnt_lo_u32_b32 v162, -1, 0
	v_mbcnt_hi_u32_b32 v162, -1, v162
	v_mov_b32_e32 v163, 0
	v_and_b32_e32 v162, 32, v162
	v_lshrrev_b32_e32 v162, 2, v162
	v_lshl_add_u64 v[130:131], v[162:163], 0, v[28:29]
	v_pk_mul_f32 v[76:77], v[76:77], v[0:1] op_sel_hi:[1,0]
	v_pk_mul_f32 v[68:69], v[68:69], v[0:1] op_sel_hi:[1,0]
	v_pk_mul_f32 v[52:53], v[52:53], v[0:1] op_sel_hi:[1,0]
	v_pk_mul_f32 v[42:43], v[42:43], v[0:1] op_sel_hi:[1,0]
	v_pk_mul_f32 v[40:41], v[40:41], v[0:1] op_sel_hi:[1,0]
	v_pk_mul_f32 v[38:39], v[38:39], v[0:1] op_sel_hi:[1,0]
	v_pk_mul_f32 v[36:37], v[36:37], v[0:1] op_sel_hi:[1,0]
	v_pk_mul_f32 v[22:23], v[22:23], v[0:1] op_sel_hi:[1,0]
	v_pk_mul_f32 v[20:21], v[20:21], v[0:1] op_sel_hi:[1,0]
	v_pk_mul_f32 v[30:31], v[30:31], v[0:1] op_sel_hi:[1,0]
	v_pk_mul_f32 v[26:27], v[26:27], v[0:1] op_sel_hi:[1,0]
	v_pk_mul_f32 v[24:25], v[24:25], v[0:1] op_sel_hi:[1,0]
	s_waitcnt vmcnt(0)
; #define GAS __attribute__((address_space(1)))
; DI unsigned pk2(float lo, float hi) { f32x2 v = {lo, hi}; bf16x2_t b = __builtin_convertvector(v, bf16x2_t); return __builtin_bit_cast(unsigned, b); }
; DI void attn_unit_d32(const Ctx& C, const bf16_t* __restrict__ Z, bf16_t* __restrict__ Y, int b, int qsel, int hsel, bool ctxq, float lam, float post_scale, const float* subln, const float mref) {
;     ...
; #pragma unroll
;         for (int d = 0; d < 4; ++d)
; #pragma unroll
;             for (int g = 0; g < 4; ++g) { const int dv = 32 * d + 8 * g + 4 * hh; const f32x4 gn = *(const GAS f32x4*)(subln + dv); const f32x4 v = r[d][g] * rs * gn;
;                 u32x2 wv; wv.x = pk2(v[0], v[1]); wv.y = pk2(v[2], v[3]); *(GAS u32x2*)(yp + dv) = wv; }
	v_pk_mul_f32 v[34:35], v[142:143], v[80:81]
	v_pk_mul_f32 v[32:33], v[140:141], v[50:51]
	v_pk_mul_f32 v[50:51], v[90:91], v[0:1] op_sel_hi:[1,0]
	v_cvt_pk_bf16_f32 v140, v32, v33
	v_cvt_pk_bf16_f32 v141, v34, v35
	v_pk_mul_f32 v[80:81], v[88:89], v[0:1] op_sel_hi:[1,0]
	v_pk_mul_f32 v[32:33], v[144:145], v[50:51]
	v_pk_mul_f32 v[34:35], v[146:147], v[80:81]
	v_cvt_pk_bf16_f32 v142, v32, v33
	v_cvt_pk_bf16_f32 v143, v34, v35
	s_nop 1
	v_permlane32_swap_b32 v140, v142
	v_permlane32_swap_b32 v141, v143
	global_store_dwordx4 v[130:131], v[140:143], off offset:3072
	v_pk_mul_f32 v[50:51], v[86:87], v[0:1] op_sel_hi:[1,0]
	v_pk_mul_f32 v[80:81], v[84:85], v[0:1] op_sel_hi:[1,0]
	v_pk_mul_f32 v[32:33], v[148:149], v[50:51]
	v_pk_mul_f32 v[34:35], v[150:151], v[80:81]
	v_cvt_pk_bf16_f32 v148, v32, v33
	v_cvt_pk_bf16_f32 v149, v34, v35
	v_pk_mul_f32 v[50:51], v[78:79], v[0:1] op_sel_hi:[1,0]
	v_pk_mul_f32 v[34:35], v[154:155], v[76:77]
	v_pk_mul_f32 v[32:33], v[152:153], v[50:51]
	v_pk_mul_f32 v[50:51], v[70:71], v[0:1] op_sel_hi:[1,0]
	v_cvt_pk_bf16_f32 v150, v32, v33
	v_cvt_pk_bf16_f32 v151, v34, v35
	s_nop 1
	v_permlane32_swap_b32 v148, v150
	v_permlane32_swap_b32 v149, v151
	global_store_dwordx4 v[130:131], v[148:151], off offset:3104
	s_nop 1
	global_load_dwordx4 v[140:143], v[170:171], off offset:416
	global_load_dwordx4 v[144:147], v[170:171], off offset:448
	global_load_dwordx4 v[148:151], v[170:171], off offset:480
	v_pk_mul_f32 v[34:35], v[160:161], v[68:69]
	v_pk_mul_f32 v[32:33], v[158:159], v[50:51]
	v_pk_mul_f32 v[50:51], v[74:75], v[0:1] op_sel_hi:[1,0]
	v_cvt_pk_bf16_f32 v158, v32, v33
	v_cvt_pk_bf16_f32 v159, v34, v35
	v_pk_mul_f32 v[68:69], v[72:73], v[0:1] op_sel_hi:[1,0]
	v_pk_mul_f32 v[32:33], v[192:193], v[50:51]
	v_pk_mul_f32 v[34:35], v[194:195], v[68:69]
	v_cvt_pk_bf16_f32 v160, v32, v33
	v_cvt_pk_bf16_f32 v161, v34, v35
	s_nop 1
	v_permlane32_swap_b32 v158, v160
	v_permlane32_swap_b32 v159, v161
	global_store_dwordx4 v[130:131], v[158:161], off offset:3136
	v_pk_mul_f32 v[50:51], v[54:55], v[0:1] op_sel_hi:[1,0]
	v_pk_mul_f32 v[34:35], v[204:205], v[52:53]
	v_pk_mul_f32 v[32:33], v[202:203], v[50:51]
	v_pk_mul_f32 v[50:51], v[66:67], v[0:1] op_sel_hi:[1,0]
	v_cvt_pk_bf16_f32 v202, v32, v33
	v_cvt_pk_bf16_f32 v203, v34, v35
	v_pk_mul_f32 v[52:53], v[64:65], v[0:1] op_sel_hi:[1,0]
	v_pk_mul_f32 v[32:33], v[50:51], v[210:211]
	v_pk_mul_f32 v[34:35], v[52:53], v[212:213]
	v_cvt_pk_bf16_f32 v204, v32, v33
	v_cvt_pk_bf16_f32 v205, v34, v35
	s_nop 1
	v_permlane32_swap_b32 v202, v204
	v_permlane32_swap_b32 v203, v205
	global_store_dwordx4 v[130:131], v[202:205], off offset:3168
	v_pk_mul_f32 v[50:51], v[62:63], v[0:1] op_sel_hi:[1,0]
	v_pk_mul_f32 v[52:53], v[60:61], v[0:1] op_sel_hi:[1,0]
	v_pk_mul_f32 v[32:33], v[50:51], v[214:215]
	v_pk_mul_f32 v[34:35], v[52:53], v[216:217]
	v_cvt_pk_bf16_f32 v214, v32, v33
	v_cvt_pk_bf16_f32 v215, v34, v35
	v_pk_mul_f32 v[50:51], v[58:59], v[0:1] op_sel_hi:[1,0]
	v_pk_mul_f32 v[52:53], v[56:57], v[0:1] op_sel_hi:[1,0]
	v_pk_mul_f32 v[32:33], v[50:51], v[218:219]
	v_pk_mul_f32 v[34:35], v[52:53], v[220:221]
	v_cvt_pk_bf16_f32 v216, v32, v33
	v_cvt_pk_bf16_f32 v217, v34, v35
	s_nop 1
	v_permlane32_swap_b32 v214, v216
	v_permlane32_swap_b32 v215, v217
	global_store_dwordx4 v[130:131], v[214:217], off offset:3200
	v_pk_mul_f32 v[34:35], v[40:41], v[224:225]
	v_pk_mul_f32 v[32:33], v[42:43], v[222:223]
	s_nop 0
	v_cvt_pk_bf16_f32 v222, v32, v33
	v_cvt_pk_bf16_f32 v223, v34, v35
	v_pk_mul_f32 v[34:35], v[36:37], v[242:243]
	v_pk_mul_f32 v[32:33], v[38:39], v[240:241]
	s_nop 0
	v_cvt_pk_bf16_f32 v224, v32, v33
	v_cvt_pk_bf16_f32 v225, v34, v35
	s_nop 1
	v_permlane32_swap_b32 v222, v224
	v_permlane32_swap_b32 v223, v225
	global_store_dwordx4 v[130:131], v[222:225], off offset:3232
	v_pk_mul_f32 v[20:21], v[20:21], v[246:247]
	v_pk_mul_f32 v[22:23], v[22:23], v[244:245]
	v_pk_mul_f32 v[32:33], v[48:49], v[0:1] op_sel_hi:[1,0]
	v_cvt_pk_bf16_f32 v244, v22, v23
	v_cvt_pk_bf16_f32 v245, v20, v21
	s_waitcnt vmcnt(4)
	v_pk_mul_f32 v[34:35], v[46:47], v[0:1] op_sel_hi:[1,0]
	v_pk_mul_f32 v[20:21], v[32:33], v[140:141]
	v_pk_mul_f32 v[22:23], v[34:35], v[142:143]
	v_cvt_pk_bf16_f32 v246, v20, v21
	v_cvt_pk_bf16_f32 v247, v22, v23
	s_nop 1
	v_permlane32_swap_b32 v244, v246
	v_permlane32_swap_b32 v245, v247
	global_store_dwordx4 v[130:131], v[244:247], off offset:3264
	v_pk_mul_f32 v[32:33], v[44:45], v[0:1] op_sel_hi:[1,0]
	v_pk_mul_f32 v[22:23], v[30:31], v[146:147]
	v_pk_mul_f32 v[20:21], v[32:33], v[144:145]
	s_nop 0
	v_cvt_pk_bf16_f32 v144, v20, v21
	v_cvt_pk_bf16_f32 v145, v22, v23
	v_pk_mul_f32 v[22:23], v[24:25], v[150:151]
	v_pk_mul_f32 v[20:21], v[26:27], v[148:149]
	s_nop 0
	v_cvt_pk_bf16_f32 v146, v20, v21
	v_cvt_pk_bf16_f32 v147, v22, v23
	s_nop 1
	v_permlane32_swap_b32 v144, v146
	v_permlane32_swap_b32 v145, v147
	global_store_dwordx4 v[130:131], v[144:147], off offset:3296
	s_branch .LBB0_396
